# score tiles remapped onto the block that produced their PEER-query columns; grid barrier between the two phases reduced to a workgroup barrier
# speedup vs baseline: 1.0828x; 1.0006x over previous
.LBB0_579:
	s_waitcnt vmcnt(0)
	s_barrier
	s_mov_b64 s[10:11], exec
	v_readlane_b32 s0, v238, 0
	v_readlane_b32 s1, v238, 1
	v_readlane_b32 s22, v236, 42
	s_and_b64 s[0:1], s[10:11], s[0:1]
	v_readlane_b32 s23, v236, 43
	s_mov_b64 exec, s[0:1]
	s_cbranch_execz .LBB0_629
	s_cmpk_eq_i32 s2, 0x200
	s_cbranch_scc1 .LBB0_629
	s_mov_b64 s[0:1], src_shared_base
	v_mov_b32_e32 v0, 0x12000
	v_mov_b32_e32 v1, s1
	s_waitcnt vmcnt(0) expcnt(0) lgkmcnt(0)
	flat_load_dword v2, v[0:1] sc0 sc1
	s_waitcnt vmcnt(0)
	v_mov_b32_e32 v0, 0x12004
	flat_load_dword v0, v[0:1] sc0 sc1
	s_waitcnt vmcnt(0) lgkmcnt(0)
	v_cmp_eq_u32_e32 vcc, 0, v2
	s_and_saveexec_b64 s[12:13], vcc
	s_cbranch_execz .LBB0_597
	s_mov_b32 s3, 1
	v_mov_b32_e32 v16, 0
	s_branch .LBB0_583

.Lq_noissue:
	s_mov_b64 vcc, s[50:51]
	s_ashr_i32 s0, s17, 31
	s_lshr_b32 s0, s0, 24
	s_add_i32 s0, s17, s0
	s_ashr_i32 s10, s0, 8
	s_and_b32 s0, s0, 0xffffff00
	s_sub_i32 s12, s17, s0
	s_ashr_i32 s13, s12, 31
	s_cmpk_lg_i32 s2, 0x200
	s_cbranch_scc1 .Lsc_std
	s_lshr_b32 s0, s17, 9
	s_and_b32 s12, s17, 0xff
	s_bfe_u32 s10, s17, 0x10008
	s_lshr_b32 s13, s0, 1
	s_lshl_b32 s13, s13, 1
	s_add_u32 s10, s10, s13
	s_lshl_b32 s10, s10, 1
	s_and_b32 s0, s0, 1
	s_add_u32 s10, s10, s0
	s_mov_b32 s13, 0
.Lsc_std:
	s_lshl_b64 s[0:1], s[12:13], 19
	s_add_u32 s11, s78, s0
	s_addc_u32 s27, s79, s1
	s_lshl_b32 s0, s10, 7
	s_ashr_i32 s1, s0, 31
	s_lshl_b64 s[0:1], s[0:1], 1
	s_add_u32 s26, s11, s0
	s_addc_u32 s27, s27, s1
	s_ashr_i32 s11, s10, 31
	s_lshl_b64 s[0:1], s[10:11], 15
	v_mov_b32 v48, v214
	s_add_u32 s0, s3, s0
	v_lshlrev_b32_e32 v0, 3, v48
	v_ashrrev_i32_e32 v1, 3, v48
	v_and_b32_e32 v49, 56, v0
	s_addc_u32 s1, s14, s1
	v_lshl_or_b32 v0, v1, 7, v49
	v_mul_lo_u32 v50, v1, s28
	v_lshl_or_b32 v98, v1, 11, v49
	v_mov_b32_e32 v1, v99
	v_lshl_add_u64 v[32:33], v[98:99], 1, s[26:27]
	v_lshl_add_u64 v[34:35], v[0:1], 1, s[0:1]
	s_mov_b32 s0, 0x20000
	v_add_co_u32_e64 v36, s[0:1], s0, v32
	global_load_dwordx4 v[0:3], v[32:33], off
	global_load_dwordx4 v[4:7], v[34:35], off
	v_addc_co_u32_e64 v37, s[0:1], 0, v33, s[0:1]
	s_movk_i32 s0, 0x2000
	s_nop 0
	v_add_co_u32_e64 v38, s[0:1], s0, v34
	global_load_dwordx4 v[8:11], v[36:37], off
	s_nop 0
	v_addc_co_u32_e64 v39, s[0:1], 0, v35, s[0:1]
	s_mov_b32 s0, 0x40000
	s_nop 0
	v_add_co_u32_e64 v40, s[0:1], s0, v32
	global_load_dwordx4 v[12:15], v[38:39], off
	s_nop 0
	v_addc_co_u32_e64 v41, s[0:1], 0, v33, s[0:1]
	s_movk_i32 s0, 0x4000
	s_nop 0
	v_add_co_u32_e64 v42, s[0:1], s0, v34
	global_load_dwordx4 v[16:19], v[40:41], off
	s_nop 0
	v_addc_co_u32_e64 v43, s[0:1], 0, v35, s[0:1]
	s_mov_b32 s0, 0x60000
	s_nop 0
	v_add_co_u32_e64 v44, s[0:1], s0, v32
	global_load_dwordx4 v[20:23], v[42:43], off
	s_nop 0
	v_addc_co_u32_e64 v45, s[0:1], 0, v33, s[0:1]
	s_movk_i32 s0, 0x6000
	global_load_dwordx4 v[28:31], v[44:45], off
	v_add_co_u32_e64 v46, s[0:1], s0, v34
	v_add_lshl_u32 v98, v50, v49, 1
	s_nop 0
	v_addc_co_u32_e64 v47, s[0:1], 0, v35, s[0:1]
	global_load_dwordx4 v[24:27], v[46:47], off
	global_load_dwordx4 v[80:83], v[32:33], off offset:128
	global_load_dwordx4 v[84:87], v[34:35], off offset:128
	global_load_dwordx4 v[88:91], v[36:37], off offset:128
	global_load_dwordx4 v[92:95], v[38:39], off offset:128
	global_load_dwordx4 v[64:67], v[40:41], off offset:128
	global_load_dwordx4 v[68:71], v[42:43], off offset:128
	global_load_dwordx4 v[72:75], v[44:45], off offset:128
	global_load_dwordx4 v[76:79], v[46:47], off offset:128
	v_and_b32_e32 v32, 31, v48
	v_lshrrev_b32_e32 v34, 1, v48
	s_mov_b32 s0, 0xfffffc0
	v_and_b32_e32 v33, 0x5f, v48
	v_and_or_b32 v35, v34, s0, v32
	v_and_b32_e32 v32, 16, v34
	s_waitcnt vmcnt(21)
	v_mad_u32_u24 v138, v33, s15, v32
	s_barrier
	v_mad_u64_u32 v[100:101], s[0:1], v35, s15, v[32:33]
	v_add_u32_e32 v101, 0xd800, v98
	s_lshl_b64 s[10:11], s[10:11], 4
	s_waitcnt vmcnt(15)
	ds_write_b128 v98, v[0:3]
	s_waitcnt vmcnt(14)
	ds_write_b128 v98, v[4:7] offset:18432
	s_waitcnt vmcnt(13)
	ds_write_b128 v98, v[8:11] offset:4608
	s_waitcnt vmcnt(12)
	ds_write_b128 v98, v[12:15] offset:23040
	s_waitcnt vmcnt(11)
	ds_write_b128 v98, v[16:19] offset:9216
	s_waitcnt vmcnt(10)
	ds_write_b128 v98, v[20:23] offset:27648
	s_waitcnt vmcnt(9)
	ds_write_b128 v98, v[28:31] offset:13824
	s_waitcnt vmcnt(8)
	ds_write_b128 v98, v[24:27] offset:32256
	s_waitcnt lgkmcnt(0)
	s_barrier
	ds_read_b128 v[16:19], v138 offset:4608
	ds_read_b128 v[20:23], v100 offset:23040
	ds_read_b128 v[0:3], v138
	ds_read_b128 v[122:125], v138 offset:32
	ds_read_b128 v[4:7], v100 offset:18432
	ds_read_b128 v[126:129], v100 offset:18464
	s_waitcnt lgkmcnt(1)
	v_mfma_f32_32x32x16_bf16 v[32:47], v[0:3], v[4:7], 0
	ds_read_b128 v[130:133], v138 offset:4640
	ds_read_b128 v[134:137], v100 offset:23072
	v_mfma_f32_32x32x16_bf16 v[48:63], v[0:3], v[20:23], 0
	v_mfma_f32_32x32x16_bf16 v[0:15], v[16:19], v[4:7], 0
	v_mfma_f32_32x32x16_bf16 v[16:31], v[16:19], v[20:23], 0
	s_waitcnt lgkmcnt(2)
	v_mfma_f32_32x32x16_bf16 v[32:47], v[122:125], v[126:129], v[32:47]
	s_waitcnt lgkmcnt(0)
	v_mfma_f32_32x32x16_bf16 v[48:63], v[122:125], v[134:137], v[48:63]
	v_mfma_f32_32x32x16_bf16 v[0:15], v[130:133], v[126:129], v[0:15]
	v_mfma_f32_32x32x16_bf16 v[16:31], v[130:133], v[134:137], v[16:31]
	ds_read_b128 v[122:125], v138 offset:64
	ds_read_b128 v[126:129], v138 offset:4672
	ds_read_b128 v[130:133], v100 offset:18496
	ds_read_b128 v[134:137], v100 offset:23104
	s_waitcnt lgkmcnt(1)
	v_mfma_f32_32x32x16_bf16 v[32:47], v[122:125], v[130:133], v[32:47]
	s_waitcnt lgkmcnt(0)
	v_mfma_f32_32x32x16_bf16 v[48:63], v[122:125], v[134:137], v[48:63]
	v_mfma_f32_32x32x16_bf16 v[0:15], v[126:129], v[130:133], v[0:15]
	v_mfma_f32_32x32x16_bf16 v[16:31], v[126:129], v[134:137], v[16:31]
	ds_read_b128 v[122:125], v138 offset:96
	ds_read_b128 v[126:129], v138 offset:4704
	ds_read_b128 v[130:133], v100 offset:18528
	ds_read_b128 v[134:137], v100 offset:23136
	s_waitcnt vmcnt(7)
	ds_write_b128 v98, v[80:83] offset:36864
	s_waitcnt vmcnt(6)
	ds_write_b128 v98, v[84:87] offset:55296
	s_waitcnt vmcnt(5)
	ds_write_b128 v98, v[88:91] offset:41472
	s_waitcnt vmcnt(4)
	ds_write_b128 v98, v[92:95] offset:59904
	s_waitcnt vmcnt(3)
	ds_write_b128 v98, v[64:67] offset:46080
	s_waitcnt vmcnt(2)
	ds_write_b128 v98, v[68:71] offset:64512
	s_waitcnt vmcnt(1)
	ds_write_b128 v98, v[72:75] offset:50688
	s_waitcnt vmcnt(0)
	ds_write_b128 v101, v[76:79] offset:13824
	s_waitcnt lgkmcnt(0)
	s_barrier
	ds_read_b128 v[64:67], v138 offset:41472
	ds_read_b128 v[68:71], v100 offset:59904
	ds_read_b128 v[72:75], v138 offset:36864
	ds_read_b128 v[76:79], v138 offset:36896
	ds_read_b128 v[80:83], v100 offset:55296
	ds_read_b128 v[84:87], v100 offset:55328
	v_mfma_f32_32x32x16_bf16 v[32:47], v[122:125], v[130:133], v[32:47]
	v_mfma_f32_32x32x16_bf16 v[48:63], v[122:125], v[134:137], v[48:63]
	v_mfma_f32_32x32x16_bf16 v[0:15], v[126:129], v[130:133], v[0:15]
	v_mfma_f32_32x32x16_bf16 v[16:31], v[126:129], v[134:137], v[16:31]
	s_waitcnt lgkmcnt(1)
	v_mfma_f32_32x32x16_bf16 v[32:47], v[72:75], v[80:83], v[32:47]
	v_mfma_f32_32x32x16_bf16 v[48:63], v[72:75], v[68:71], v[48:63]
	v_mfma_f32_32x32x16_bf16 v[0:15], v[64:67], v[80:83], v[0:15]
	v_mfma_f32_32x32x16_bf16 v[16:31], v[64:67], v[68:71], v[16:31]
	ds_read_b128 v[64:67], v138 offset:41504
	ds_read_b128 v[68:71], v100 offset:59936
	s_waitcnt lgkmcnt(2)
	v_mfma_f32_32x32x16_bf16 v[32:47], v[76:79], v[84:87], v[32:47]
	s_waitcnt lgkmcnt(0)
	v_mfma_f32_32x32x16_bf16 v[48:63], v[76:79], v[68:71], v[48:63]
	v_mfma_f32_32x32x16_bf16 v[0:15], v[64:67], v[84:87], v[0:15]
	v_mfma_f32_32x32x16_bf16 v[16:31], v[64:67], v[68:71], v[16:31]
	ds_read_b128 v[64:67], v138 offset:36928
	ds_read_b128 v[68:71], v138 offset:41536
	ds_read_b128 v[72:75], v100 offset:55360
	ds_read_b128 v[76:79], v100 offset:59968
	s_waitcnt lgkmcnt(1)
	v_mfma_f32_32x32x16_bf16 v[32:47], v[64:67], v[72:75], v[32:47]
	s_waitcnt lgkmcnt(0)
	v_mfma_f32_32x32x16_bf16 v[48:63], v[64:67], v[76:79], v[48:63]
	v_mfma_f32_32x32x16_bf16 v[0:15], v[68:71], v[72:75], v[0:15]
	v_mfma_f32_32x32x16_bf16 v[16:31], v[68:71], v[76:79], v[16:31]
	ds_read_b128 v[64:67], v138 offset:36960
	ds_read_b128 v[68:71], v138 offset:41568
	ds_read_b128 v[72:75], v100 offset:55392
	ds_read_b128 v[76:79], v100 offset:60000
	s_waitcnt lgkmcnt(1)
	v_mfma_f32_32x32x16_bf16 v[32:47], v[64:67], v[72:75], v[32:47]
	s_waitcnt lgkmcnt(0)
	v_mfma_f32_32x32x16_bf16 v[48:63], v[64:67], v[76:79], v[48:63]
	v_mov_b32 v64, v214
	v_mov_b32 v65, v214
	s_nop 0
	v_lshrrev_b32_e32 v66, 3, v64
	v_and_b32_e32 v66, 4, v66
	v_and_or_b32 v66, v65, 64, v66
	v_lshlrev_b32_e32 v65, 1, v65
	v_and_b32_e32 v64, 31, v64
	v_mul_u32_u24_e32 v66, 0x210, v66
	v_and_b32_e32 v65, 0xffffff00, v65
	v_lshlrev_b32_e32 v64, 2, v64
	v_add3_u32 v64, v66, v65, v64
	s_barrier
	s_nop 0
	ds_write2_b32 v64, v32, v48 offset1:32
	ds_write2_b32 v64, v33, v49 offset0:132 offset1:164
	v_add_u32_e32 v32, 0x400, v64
	ds_write2_b32 v32, v34, v50 offset0:8 offset1:40
	ds_write2_b32 v32, v35, v51 offset0:140 offset1:172
	v_add_u32_e32 v32, 0x1000, v64
	v_mfma_f32_32x32x16_bf16 v[0:15], v[68:71], v[72:75], v[0:15]
	ds_write2_b32 v32, v36, v52 offset0:32 offset1:64
	ds_write2_b32 v32, v37, v53 offset0:164 offset1:196
	v_add_u32_e32 v32, 0x1400, v64
	ds_write2_b32 v32, v38, v54 offset0:40 offset1:72
	ds_write2_b32 v32, v39, v55 offset0:172 offset1:204
	v_add_u32_e32 v32, 0x2000, v64
	ds_write2_b32 v32, v40, v56 offset0:64 offset1:96
	ds_write2_b32 v32, v41, v57 offset0:196 offset1:228
	v_add_u32_e32 v32, 0x2400, v64
	ds_write2_b32 v32, v42, v58 offset0:72 offset1:104
	ds_write2_b32 v32, v43, v59 offset0:204 offset1:236
	v_mfma_f32_32x32x16_bf16 v[16:31], v[68:71], v[76:79], v[16:31]
	v_add_u32_e32 v32, 0x3000, v64
	ds_write2_b32 v32, v44, v60 offset0:96 offset1:128
	v_add_u32_e32 v32, 0x3200, v64
	ds_write2_b32 v32, v45, v61 offset0:100 offset1:132
	v_add_u32_e32 v32, 0x3400, v64
	ds_write2_b32 v32, v46, v62 offset0:104 offset1:136
	v_add_u32_e32 v32, 0x3600, v64
	ds_write2_b32 v32, v47, v63 offset0:108 offset1:140
	v_add_u32_e32 v32, 0x4000, v64
	s_nop 2
	ds_write2_b32 v32, v0, v16 offset0:128 offset1:160
	v_add_u32_e32 v0, 0x4400, v64
	ds_write2_b32 v0, v1, v17 offset0:4 offset1:36
	ds_write2_b32 v0, v2, v18 offset0:136 offset1:168
	v_add_u32_e32 v0, 0x4800, v64
	ds_write2_b32 v0, v3, v19 offset0:12 offset1:44
	v_add_u32_e32 v0, 0x5000, v64
	ds_write2_b32 v0, v4, v20 offset0:160 offset1:192
	v_add_u32_e32 v0, 0x5400, v64
	ds_write2_b32 v0, v5, v21 offset0:36 offset1:68
	ds_write2_b32 v0, v6, v22 offset0:168 offset1:200
	v_add_u32_e32 v0, 0x5800, v64
	ds_write2_b32 v0, v7, v23 offset0:44 offset1:76
	v_add_u32_e32 v0, 0x6000, v64
	ds_write2_b32 v0, v8, v24 offset0:192 offset1:224
	v_add_u32_e32 v0, 0x6400, v64
	ds_write2_b32 v0, v9, v25 offset0:68 offset1:100
	ds_write2_b32 v0, v10, v26 offset0:200 offset1:232
	v_add_u32_e32 v0, 0x6800, v64
	ds_write2_b32 v0, v11, v27 offset0:76 offset1:108
	v_add_u32_e32 v0, 0x7200, v64
	ds_write2_b32 v0, v12, v28 offset0:96 offset1:128
	v_add_u32_e32 v0, 0x7400, v64
	ds_write2_b32 v0, v13, v29 offset0:100 offset1:132
	v_add_u32_e32 v0, 0x7600, v64
	ds_write2_b32 v0, v14, v30 offset0:104 offset1:136
	v_add_u32_e32 v0, 0x7800, v64
	ds_write2_b32 v0, v15, v31 offset0:108 offset1:140
	s_waitcnt lgkmcnt(0)
	s_barrier
	ds_read_b128 v[8:11], v104 offset:64
	ds_read_b128 v[16:19], v104 offset:128
	ds_read_b128 v[26:29], v104 offset:192
	ds_read_b128 v[30:33], v104
	ds_read_b128 v[34:37], v104 offset:16
	ds_read_b128 v[4:7], v104 offset:32
	ds_read_b128 v[0:3], v104 offset:48
	s_waitcnt lgkmcnt(3)
	v_not_b32_e32 v12, v30
	v_or_b32_e32 v13, 0x80000000, v30
	v_cmp_gt_i32_e64 s[0:1], 0, v30
	s_waitcnt lgkmcnt(2)
	v_or_b32_e32 v15, 0x80000000, v35
	v_or_b32_e32 v25, 0x80000000, v37
	v_cndmask_b32_e64 v12, v13, v12, s[0:1]
	v_and_b32_e32 v12, 0xffffff80, v12
	v_sub_u32_e32 v12, v12, v103
	v_add_u32_e32 v46, 0x7f, v12
	v_not_b32_e32 v12, v8
	v_or_b32_e32 v13, 0x80000000, v8
	v_cmp_gt_i32_e64 s[0:1], 0, v8
	s_waitcnt lgkmcnt(0)
	v_not_b32_e32 v64, v0
	v_or_b32_e32 v65, 0x80000000, v0
	v_cndmask_b32_e64 v8, v13, v12, s[0:1]
	v_and_b32_e32 v8, 0xffffff80, v8
	v_sub_u32_e32 v8, v8, v103
	v_add_u32_e32 v22, 0x6f, v8
	v_not_b32_e32 v8, v16
	v_or_b32_e32 v12, 0x80000000, v16
	v_cmp_gt_i32_e64 s[0:1], 0, v16
	v_or_b32_e32 v13, 0x80000000, v31
	s_nop 0
	v_cndmask_b32_e64 v8, v12, v8, s[0:1]
	v_and_b32_e32 v8, 0xffffff80, v8
	v_sub_u32_e32 v8, v8, v103
	v_add_u32_e32 v14, 0x5f, v8
	v_not_b32_e32 v8, v26
	v_or_b32_e32 v12, 0x80000000, v26
	v_cmp_gt_i32_e64 s[0:1], 0, v26
	s_nop 1
	v_cndmask_b32_e64 v8, v12, v8, s[0:1]
	v_not_b32_e32 v12, v31
	v_cmp_gt_i32_e64 s[0:1], 0, v31
	v_and_b32_e32 v8, 0xffffff80, v8
	v_sub_u32_e32 v8, v8, v103
	v_cndmask_b32_e64 v12, v13, v12, s[0:1]
	v_and_b32_e32 v12, 0xffffff80, v12
	v_sub_u32_e32 v12, v12, v105
	v_add_u32_e32 v47, 0x7f, v12
	v_not_b32_e32 v12, v9
	v_or_b32_e32 v13, 0x80000000, v9
	v_cmp_gt_i32_e64 s[0:1], 0, v9
	v_add_u32_e32 v8, 0x4f, v8
	s_nop 0
	v_cndmask_b32_e64 v9, v13, v12, s[0:1]
	v_and_b32_e32 v9, 0xffffff80, v9
	v_sub_u32_e32 v9, v9, v105
	v_add_u32_e32 v24, 0x6f, v9
	v_not_b32_e32 v9, v17
	v_or_b32_e32 v12, 0x80000000, v17
	v_cmp_gt_i32_e64 s[0:1], 0, v17
	v_or_b32_e32 v13, 0x80000000, v32
	v_or_b32_e32 v17, 0x80000000, v36
	v_cndmask_b32_e64 v9, v12, v9, s[0:1]
	v_and_b32_e32 v9, 0xffffff80, v9
	v_sub_u32_e32 v9, v9, v105
	v_add_u32_e32 v16, 0x5f, v9
	v_not_b32_e32 v9, v27
	v_or_b32_e32 v12, 0x80000000, v27
	v_cmp_gt_i32_e64 s[0:1], 0, v27
	v_max_u32_e32 v72, v22, v24
	v_min_u32_e32 v22, v22, v24
	v_cndmask_b32_e64 v9, v12, v9, s[0:1]
	v_not_b32_e32 v12, v32
	v_cmp_gt_i32_e64 s[0:1], 0, v32
	v_and_b32_e32 v9, 0xffffff80, v9
	v_sub_u32_e32 v9, v9, v105
	v_cndmask_b32_e64 v12, v13, v12, s[0:1]
	v_and_b32_e32 v12, 0xffffff80, v12
	v_sub_u32_e32 v12, v12, v106
	v_add_u32_e32 v48, 0x7f, v12
	v_not_b32_e32 v12, v10
	v_or_b32_e32 v13, 0x80000000, v10
	v_cmp_gt_i32_e64 s[0:1], 0, v10
	v_add_u32_e32 v9, 0x4f, v9
	v_max_u32_e32 v80, v14, v16
	v_cndmask_b32_e64 v10, v13, v12, s[0:1]
	v_and_b32_e32 v10, 0xffffff80, v10
	v_sub_u32_e32 v10, v10, v106
	v_add_u32_e32 v26, 0x6f, v10
	v_not_b32_e32 v10, v18
	v_or_b32_e32 v12, 0x80000000, v18
	v_cmp_gt_i32_e64 s[0:1], 0, v18
	v_or_b32_e32 v13, 0x80000000, v33
	v_min_u32_e32 v14, v14, v16
	v_cndmask_b32_e64 v10, v12, v10, s[0:1]
	v_and_b32_e32 v10, 0xffffff80, v10
	v_sub_u32_e32 v10, v10, v106
	v_add_u32_e32 v18, 0x5f, v10
	v_not_b32_e32 v10, v28
	v_or_b32_e32 v12, 0x80000000, v28
	v_cmp_gt_i32_e64 s[0:1], 0, v28
	v_max_u32_e32 v88, v8, v9
	v_min_u32_e32 v8, v8, v9
	v_cndmask_b32_e64 v10, v12, v10, s[0:1]
	v_not_b32_e32 v12, v33
	v_cmp_gt_i32_e64 s[0:1], 0, v33
	ds_read_b128 v[30:33], v104 offset:80
	ds_read_b128 v[38:41], v104 offset:144
	ds_read_b128 v[42:45], v104 offset:208
	v_cndmask_b32_e64 v12, v13, v12, s[0:1]
	v_and_b32_e32 v12, 0xffffff80, v12
	v_sub_u32_e32 v12, v12, v107
	v_add_u32_e32 v49, 0x7f, v12
	v_not_b32_e32 v12, v11
	v_or_b32_e32 v13, 0x80000000, v11
	v_cmp_gt_i32_e64 s[0:1], 0, v11
	s_waitcnt lgkmcnt(0)
	v_or_b32_e32 v27, 0x80000000, v45
	v_and_b32_e32 v10, 0xffffff80, v10
	v_cndmask_b32_e64 v11, v13, v12, s[0:1]
	v_and_b32_e32 v11, 0xffffff80, v11
	v_sub_u32_e32 v11, v11, v107
	v_add_u32_e32 v28, 0x6f, v11
	v_not_b32_e32 v11, v19
	v_or_b32_e32 v12, 0x80000000, v19
	v_cmp_gt_i32_e64 s[0:1], 0, v19
	v_or_b32_e32 v13, 0x80000000, v34
	v_sub_u32_e32 v10, v10, v106
	v_cndmask_b32_e64 v11, v12, v11, s[0:1]
	v_and_b32_e32 v11, 0xffffff80, v11
	v_sub_u32_e32 v11, v11, v107
	v_add_u32_e32 v19, 0x5f, v11
	v_not_b32_e32 v11, v29
	v_or_b32_e32 v12, 0x80000000, v29
	v_cmp_gt_i32_e64 s[0:1], 0, v29
	v_add_u32_e32 v10, 0x4f, v10
	v_max_u32_e32 v24, v28, v26
	v_cndmask_b32_e64 v11, v12, v11, s[0:1]
	v_not_b32_e32 v12, v34
	v_cmp_gt_i32_e64 s[0:1], 0, v34
	v_and_b32_e32 v11, 0xffffff80, v11
	v_sub_u32_e32 v11, v11, v107
	v_cndmask_b32_e64 v12, v13, v12, s[0:1]
	v_and_b32_e32 v12, 0xffffff80, v12
	v_sub_u32_e32 v12, v12, v108
	v_add_u32_e32 v29, 0x7f, v12
	v_not_b32_e32 v12, v30
	v_or_b32_e32 v13, 0x80000000, v30
	v_cmp_gt_i32_e64 s[0:1], 0, v30
	v_add_u32_e32 v11, 0x4f, v11
	v_min_u32_e32 v26, v28, v26
	v_cndmask_b32_e64 v12, v13, v12, s[0:1]
	v_and_b32_e32 v12, 0xffffff80, v12
	v_sub_u32_e32 v12, v12, v108
	v_add_u32_e32 v50, 0x6f, v12
	v_not_b32_e32 v12, v38
	v_or_b32_e32 v13, 0x80000000, v38
	v_cmp_gt_i32_e64 s[0:1], 0, v38
	v_max_u32_e32 v16, v19, v18
	v_min_u32_e32 v18, v19, v18
	v_cndmask_b32_e64 v12, v13, v12, s[0:1]
	v_and_b32_e32 v12, 0xffffff80, v12
	v_sub_u32_e32 v12, v12, v108
	v_add_u32_e32 v20, 0x5f, v12
	v_not_b32_e32 v12, v42
	v_or_b32_e32 v13, 0x80000000, v42
	v_cmp_gt_i32_e64 s[0:1], 0, v42
	v_max_u32_e32 v9, v11, v10
	v_min_u32_e32 v10, v11, v10
	v_cndmask_b32_e64 v12, v13, v12, s[0:1]
	v_not_b32_e32 v13, v35
	v_cmp_gt_i32_e64 s[0:1], 0, v35
	v_and_b32_e32 v12, 0xffffff80, v12
	v_sub_u32_e32 v12, v12, v108
	v_cndmask_b32_e64 v13, v15, v13, s[0:1]
	v_and_b32_e32 v13, 0xffffff80, v13
	v_sub_u32_e32 v13, v13, v109
	v_add_u32_e32 v42, 0x7f, v13
	v_not_b32_e32 v13, v31
	v_or_b32_e32 v15, 0x80000000, v31
	v_cmp_gt_i32_e64 s[0:1], 0, v31
	v_add_u32_e32 v12, 0x4f, v12
	s_nop 0
	v_cndmask_b32_e64 v13, v15, v13, s[0:1]
	v_and_b32_e32 v13, 0xffffff80, v13
	v_sub_u32_e32 v13, v13, v109
	v_add_u32_e32 v51, 0x6f, v13
	v_not_b32_e32 v13, v39
	v_or_b32_e32 v15, 0x80000000, v39
	v_cmp_gt_i32_e64 s[0:1], 0, v39
	v_max_u32_e32 v28, v50, v51
	v_min_u32_e32 v50, v50, v51
	v_cndmask_b32_e64 v13, v15, v13, s[0:1]
	v_and_b32_e32 v13, 0xffffff80, v13
	v_sub_u32_e32 v13, v13, v109
	v_add_u32_e32 v21, 0x5f, v13
	v_not_b32_e32 v13, v43
	v_or_b32_e32 v15, 0x80000000, v43
	v_cmp_gt_i32_e64 s[0:1], 0, v43
	v_max_u32_e32 v19, v20, v21
	v_min_u32_e32 v20, v20, v21
	v_cndmask_b32_e64 v13, v15, v13, s[0:1]
	v_not_b32_e32 v15, v36
	v_cmp_gt_i32_e64 s[0:1], 0, v36
	v_and_b32_e32 v13, 0xffffff80, v13
	v_sub_u32_e32 v13, v13, v109
	v_cndmask_b32_e64 v15, v17, v15, s[0:1]
	v_and_b32_e32 v15, 0xffffff80, v15
	v_sub_u32_e32 v15, v15, v110
	v_add_u32_e32 v43, 0x7f, v15
	v_not_b32_e32 v15, v32
	v_or_b32_e32 v17, 0x80000000, v32
	v_cmp_gt_i32_e64 s[0:1], 0, v32
	v_add_u32_e32 v13, 0x4f, v13
	v_max_u32_e32 v11, v12, v13
	v_cndmask_b32_e64 v15, v17, v15, s[0:1]
	v_and_b32_e32 v15, 0xffffff80, v15
	v_sub_u32_e32 v15, v15, v110
	v_add_u32_e32 v52, 0x6f, v15
	v_not_b32_e32 v15, v40
	v_or_b32_e32 v17, 0x80000000, v40
	v_cmp_gt_i32_e64 s[0:1], 0, v40
	v_min_u32_e32 v12, v12, v13
	s_nop 0
	v_cndmask_b32_e64 v15, v17, v15, s[0:1]
	v_and_b32_e32 v15, 0xffffff80, v15
	v_sub_u32_e32 v15, v15, v110
	v_add_u32_e32 v23, 0x5f, v15
	v_not_b32_e32 v15, v44
	v_or_b32_e32 v17, 0x80000000, v44
	v_cmp_gt_i32_e64 s[0:1], 0, v44
	s_nop 1
	v_cndmask_b32_e64 v15, v17, v15, s[0:1]
	v_not_b32_e32 v17, v37
	v_cmp_gt_i32_e64 s[0:1], 0, v37
	v_and_b32_e32 v15, 0xffffff80, v15
	v_sub_u32_e32 v15, v15, v110
	v_cndmask_b32_e64 v17, v25, v17, s[0:1]
	v_and_b32_e32 v17, 0xffffff80, v17
	v_sub_u32_e32 v17, v17, v111
	v_add_u32_e32 v44, 0x7f, v17
	v_not_b32_e32 v17, v33
	v_or_b32_e32 v25, 0x80000000, v33
	v_cmp_gt_i32_e64 s[0:1], 0, v33
	v_add_u32_e32 v15, 0x4f, v15
	s_nop 0
	v_cndmask_b32_e64 v17, v25, v17, s[0:1]
	v_and_b32_e32 v17, 0xffffff80, v17
	v_sub_u32_e32 v17, v17, v111
	v_add_u32_e32 v53, 0x6f, v17
	v_not_b32_e32 v17, v41
	v_or_b32_e32 v25, 0x80000000, v41
	v_cmp_gt_i32_e64 s[0:1], 0, v41
	ds_read_b128 v[30:33], v104 offset:96
	ds_read_b128 v[34:37], v104 offset:160
	ds_read_b128 v[38:41], v104 offset:224
	v_cndmask_b32_e64 v17, v25, v17, s[0:1]
	v_and_b32_e32 v17, 0xffffff80, v17
	v_sub_u32_e32 v17, v17, v111
	v_add_u32_e32 v25, 0x5f, v17
	v_not_b32_e32 v17, v45
	v_cmp_gt_i32_e64 s[0:1], 0, v45
	v_or_b32_e32 v45, 0x80000000, v4
	v_max_u32_e32 v51, v53, v52
	v_cndmask_b32_e64 v17, v27, v17, s[0:1]
	v_not_b32_e32 v27, v4
	v_cmp_gt_i32_e64 s[0:1], 0, v4
	v_and_b32_e32 v17, 0xffffff80, v17
	v_sub_u32_e32 v17, v17, v111
	v_cndmask_b32_e64 v4, v45, v27, s[0:1]
	v_and_b32_e32 v4, 0xffffff80, v4
	v_sub_u32_e32 v4, v4, v112
	v_add_u32_e32 v45, 0x7f, v4
	s_waitcnt lgkmcnt(2)
	v_not_b32_e32 v4, v30
	v_or_b32_e32 v27, 0x80000000, v30
	v_cmp_gt_i32_e64 s[0:1], 0, v30
	s_waitcnt lgkmcnt(0)
	v_or_b32_e32 v30, 0x80000000, v38
	v_add_u32_e32 v17, 0x4f, v17
	v_cndmask_b32_e64 v4, v27, v4, s[0:1]
	v_and_b32_e32 v4, 0xffffff80, v4
	v_sub_u32_e32 v4, v4, v112
	v_add_u32_e32 v54, 0x6f, v4
	v_not_b32_e32 v4, v34
	v_or_b32_e32 v27, 0x80000000, v34
	v_cmp_gt_i32_e64 s[0:1], 0, v34
	v_or_b32_e32 v34, 0x80000000, v5
	v_min_u32_e32 v52, v53, v52
	v_cndmask_b32_e64 v4, v27, v4, s[0:1]
	v_and_b32_e32 v4, 0xffffff80, v4
	v_sub_u32_e32 v4, v4, v112
	v_add_u32_e32 v27, 0x5f, v4
	v_not_b32_e32 v4, v38
	v_cmp_gt_i32_e64 s[0:1], 0, v38
	v_max_u32_e32 v21, v25, v23
	v_min_u32_e32 v23, v25, v23
	v_cndmask_b32_e64 v4, v30, v4, s[0:1]
	v_not_b32_e32 v30, v5
	v_cmp_gt_i32_e64 s[0:1], 0, v5
	v_and_b32_e32 v4, 0xffffff80, v4
	v_sub_u32_e32 v4, v4, v112
	v_cndmask_b32_e64 v5, v34, v30, s[0:1]
	v_and_b32_e32 v5, 0xffffff80, v5
	v_sub_u32_e32 v5, v5, v113
	v_add_u32_e32 v55, 0x7f, v5
	v_not_b32_e32 v5, v31
	v_or_b32_e32 v30, 0x80000000, v31
	v_cmp_gt_i32_e64 s[0:1], 0, v31
	v_or_b32_e32 v31, 0x80000000, v6
	v_add_u32_e32 v4, 0x4f, v4
	v_cndmask_b32_e64 v5, v30, v5, s[0:1]
	v_and_b32_e32 v5, 0xffffff80, v5
	v_sub_u32_e32 v5, v5, v113
	v_add_u32_e32 v56, 0x6f, v5
	v_not_b32_e32 v5, v35
	v_or_b32_e32 v30, 0x80000000, v35
	v_cmp_gt_i32_e64 s[0:1], 0, v35
	v_max_u32_e32 v53, v54, v56
	v_min_u32_e32 v54, v54, v56
	v_cndmask_b32_e64 v5, v30, v5, s[0:1]
	v_and_b32_e32 v5, 0xffffff80, v5
	v_sub_u32_e32 v5, v5, v113
	v_add_u32_e32 v57, 0x5f, v5
	v_not_b32_e32 v5, v39
	v_or_b32_e32 v30, 0x80000000, v39
	v_cmp_gt_i32_e64 s[0:1], 0, v39
	v_max_u32_e32 v25, v27, v57
	v_min_u32_e32 v27, v27, v57
	v_cndmask_b32_e64 v5, v30, v5, s[0:1]
	v_not_b32_e32 v30, v6
	v_cmp_gt_i32_e64 s[0:1], 0, v6
	v_and_b32_e32 v5, 0xffffff80, v5
	v_sub_u32_e32 v5, v5, v113
	v_cndmask_b32_e64 v6, v31, v30, s[0:1]
	v_and_b32_e32 v6, 0xffffff80, v6
	v_sub_u32_e32 v6, v6, v114
	v_add_u32_e32 v58, 0x7f, v6
	v_not_b32_e32 v6, v32
	v_or_b32_e32 v30, 0x80000000, v32
	v_cmp_gt_i32_e64 s[0:1], 0, v32
	v_or_b32_e32 v31, 0x80000000, v7
	v_add_u32_e32 v5, 0x4f, v5
	v_cndmask_b32_e64 v6, v30, v6, s[0:1]
	v_and_b32_e32 v6, 0xffffff80, v6
	v_sub_u32_e32 v6, v6, v114
	v_add_u32_e32 v59, 0x6f, v6
	v_not_b32_e32 v6, v36
	v_or_b32_e32 v30, 0x80000000, v36
	v_cmp_gt_i32_e64 s[0:1], 0, v36
	v_max_u32_e32 v13, v17, v15
	v_min_u32_e32 v15, v17, v15
	v_cndmask_b32_e64 v6, v30, v6, s[0:1]
	v_and_b32_e32 v6, 0xffffff80, v6
	v_sub_u32_e32 v6, v6, v114
	v_add_u32_e32 v60, 0x5f, v6
	v_not_b32_e32 v6, v40
	v_or_b32_e32 v30, 0x80000000, v40
	v_cmp_gt_i32_e64 s[0:1], 0, v40
	v_max_u32_e32 v17, v4, v5
	v_min_u32_e32 v4, v4, v5
	v_cndmask_b32_e64 v6, v30, v6, s[0:1]
	v_not_b32_e32 v30, v7
	v_cmp_gt_i32_e64 s[0:1], 0, v7
	v_and_b32_e32 v6, 0xffffff80, v6
	v_sub_u32_e32 v6, v6, v114
	v_cndmask_b32_e64 v7, v31, v30, s[0:1]
	v_and_b32_e32 v7, 0xffffff80, v7
	v_sub_u32_e32 v7, v7, v115
	v_add_u32_e32 v61, 0x7f, v7
	v_not_b32_e32 v7, v33
	v_or_b32_e32 v30, 0x80000000, v33
	v_cmp_gt_i32_e64 s[0:1], 0, v33
	v_add_u32_e32 v6, 0x4f, v6
	s_nop 0
	v_cndmask_b32_e64 v7, v30, v7, s[0:1]
	v_and_b32_e32 v7, 0xffffff80, v7
	v_sub_u32_e32 v7, v7, v115
	v_add_u32_e32 v62, 0x6f, v7
	v_not_b32_e32 v7, v37
	v_or_b32_e32 v30, 0x80000000, v37
	v_cmp_gt_i32_e64 s[0:1], 0, v37
	v_max_u32_e32 v56, v62, v59
	v_min_u32_e32 v59, v62, v59
	v_cndmask_b32_e64 v7, v30, v7, s[0:1]
	v_and_b32_e32 v7, 0xffffff80, v7
	v_sub_u32_e32 v7, v7, v115
	v_add_u32_e32 v63, 0x5f, v7
	v_not_b32_e32 v7, v41
	v_or_b32_e32 v30, 0x80000000, v41
	v_cmp_gt_i32_e64 s[0:1], 0, v41
	v_max_u32_e32 v57, v63, v60
	v_min_u32_e32 v60, v63, v60
	v_cndmask_b32_e64 v7, v30, v7, s[0:1]
	v_cmp_gt_i32_e64 s[0:1], 0, v0
	ds_read_b128 v[30:33], v104 offset:112
	ds_read_b128 v[34:37], v104 offset:176
	ds_read_b128 v[38:41], v104 offset:240
	v_cndmask_b32_e64 v0, v65, v64, s[0:1]
	v_and_b32_e32 v0, 0xffffff80, v0
	v_sub_u32_e32 v0, v0, v116
	v_add_u32_e32 v64, 0x7f, v0
	s_waitcnt lgkmcnt(2)
	v_not_b32_e32 v0, v30
	v_or_b32_e32 v65, 0x80000000, v30
	v_cmp_gt_i32_e64 s[0:1], 0, v30
	v_and_b32_e32 v7, 0xffffff80, v7
	v_sub_u32_e32 v7, v7, v115
	v_cndmask_b32_e64 v0, v65, v0, s[0:1]
	v_and_b32_e32 v0, 0xffffff80, v0
	v_sub_u32_e32 v0, v0, v116
	v_add_u32_e32 v30, 0x6f, v0
	s_waitcnt lgkmcnt(1)
	v_not_b32_e32 v0, v34
	v_or_b32_e32 v65, 0x80000000, v34
	v_cmp_gt_i32_e64 s[0:1], 0, v34
	v_add_u32_e32 v7, 0x4f, v7
	v_max_u32_e32 v5, v7, v6
	v_cndmask_b32_e64 v0, v65, v0, s[0:1]
	v_and_b32_e32 v0, 0xffffff80, v0
	v_sub_u32_e32 v0, v0, v116
	v_add_u32_e32 v34, 0x5f, v0
	s_waitcnt lgkmcnt(0)
	v_not_b32_e32 v0, v38
	v_or_b32_e32 v65, 0x80000000, v38
	v_cmp_gt_i32_e64 s[0:1], 0, v38
	v_not_b32_e32 v38, v1
	v_min_u32_e32 v6, v7, v6
	v_cndmask_b32_e64 v0, v65, v0, s[0:1]
	v_or_b32_e32 v65, 0x80000000, v1
	v_cmp_gt_i32_e64 s[0:1], 0, v1
	v_and_b32_e32 v0, 0xffffff80, v0
	v_sub_u32_e32 v0, v0, v116
	v_cndmask_b32_e64 v1, v65, v38, s[0:1]
	v_and_b32_e32 v1, 0xffffff80, v1
	v_sub_u32_e32 v1, v1, v117
	v_add_u32_e32 v38, 0x7f, v1
	v_not_b32_e32 v1, v31
	v_or_b32_e32 v65, 0x80000000, v31
	v_cmp_gt_i32_e64 s[0:1], 0, v31
	v_add_u32_e32 v0, 0x4f, v0
	s_nop 0
	v_cndmask_b32_e64 v1, v65, v1, s[0:1]
	v_and_b32_e32 v1, 0xffffff80, v1
	v_sub_u32_e32 v1, v1, v117
	v_add_u32_e32 v31, 0x6f, v1
	v_not_b32_e32 v1, v35
	v_or_b32_e32 v65, 0x80000000, v35
	v_cmp_gt_i32_e64 s[0:1], 0, v35
	v_max_u32_e32 v62, v30, v31
	v_min_u32_e32 v30, v30, v31
	v_cndmask_b32_e64 v1, v65, v1, s[0:1]
	v_and_b32_e32 v1, 0xffffff80, v1
	v_sub_u32_e32 v1, v1, v117
	v_add_u32_e32 v35, 0x5f, v1
	v_not_b32_e32 v1, v39
	v_or_b32_e32 v65, 0x80000000, v39
	v_cmp_gt_i32_e64 s[0:1], 0, v39
	v_not_b32_e32 v39, v2
	v_max_u32_e32 v63, v34, v35
	v_cndmask_b32_e64 v1, v65, v1, s[0:1]
	v_or_b32_e32 v65, 0x80000000, v2
	v_cmp_gt_i32_e64 s[0:1], 0, v2
	v_and_b32_e32 v1, 0xffffff80, v1
	v_sub_u32_e32 v1, v1, v117
	v_cndmask_b32_e64 v2, v65, v39, s[0:1]
	v_not_b32_e32 v39, v32
	v_or_b32_e32 v65, 0x80000000, v32
	v_cmp_gt_i32_e64 s[0:1], 0, v32
	v_and_b32_e32 v2, 0xffffff80, v2
	v_sub_u32_e32 v2, v2, v118
	v_cndmask_b32_e64 v32, v65, v39, s[0:1]
	v_not_b32_e32 v39, v36
	v_or_b32_e32 v65, 0x80000000, v36
	v_cmp_gt_i32_e64 s[0:1], 0, v36
	v_and_b32_e32 v32, 0xffffff80, v32
	v_sub_u32_e32 v32, v32, v118
	v_cndmask_b32_e64 v36, v65, v39, s[0:1]
	v_not_b32_e32 v39, v40
	v_or_b32_e32 v65, 0x80000000, v40
	v_cmp_gt_i32_e64 s[0:1], 0, v40
	v_not_b32_e32 v40, v3
	v_and_b32_e32 v36, 0xffffff80, v36
	v_cndmask_b32_e64 v39, v65, v39, s[0:1]
	v_or_b32_e32 v65, 0x80000000, v3
	v_cmp_gt_i32_e64 s[0:1], 0, v3
	v_and_b32_e32 v39, 0xffffff80, v39
	v_sub_u32_e32 v36, v36, v118
	v_cndmask_b32_e64 v3, v65, v40, s[0:1]
	v_not_b32_e32 v40, v33
	v_or_b32_e32 v65, 0x80000000, v33
	v_cmp_gt_i32_e64 s[0:1], 0, v33
	v_and_b32_e32 v3, 0xffffff80, v3
	v_sub_u32_e32 v39, v39, v118
	v_cndmask_b32_e64 v33, v65, v40, s[0:1]
	v_not_b32_e32 v40, v37
	v_or_b32_e32 v65, 0x80000000, v37
	v_cmp_gt_i32_e64 s[0:1], 0, v37
	v_and_b32_e32 v33, 0xffffff80, v33
	v_sub_u32_e32 v3, v3, v119
	v_cndmask_b32_e64 v37, v65, v40, s[0:1]
	v_not_b32_e32 v40, v41
	v_or_b32_e32 v65, 0x80000000, v41
	v_cmp_gt_i32_e64 s[0:1], 0, v41
	v_and_b32_e32 v37, 0xffffff80, v37
	v_sub_u32_e32 v33, v33, v119
	v_cndmask_b32_e64 v40, v65, v40, s[0:1]
	v_and_b32_e32 v40, 0xffffff80, v40
	v_sub_u32_e32 v37, v37, v119
	v_sub_u32_e32 v40, v40, v119
	v_add_u32_e32 v1, 0x4f, v1
	v_add_u32_e32 v2, 0x7f, v2
	v_add_u32_e32 v32, 0x6f, v32
	v_add_u32_e32 v36, 0x5f, v36
	v_add_u32_e32 v39, 0x4f, v39
	v_add_u32_e32 v3, 0x7f, v3
	v_add_u32_e32 v33, 0x6f, v33
	v_add_u32_e32 v37, 0x5f, v37
	v_add_u32_e32 v40, 0x4f, v40
	v_max_u32_e32 v41, v46, v47
	v_min_u32_e32 v46, v46, v47
	v_max_u32_e32 v47, v49, v48
	v_min_u32_e32 v48, v49, v48
	v_max_u32_e32 v49, v29, v42
	v_min_u32_e32 v29, v29, v42
	v_max_u32_e32 v42, v44, v43
	v_min_u32_e32 v43, v44, v43
	v_max_u32_e32 v44, v45, v55
	v_min_u32_e32 v45, v45, v55
	v_max_u32_e32 v55, v61, v58
	v_min_u32_e32 v58, v61, v58
	v_max_u32_e32 v61, v64, v38
	v_min_u32_e32 v38, v64, v38
	v_max_u32_e32 v64, v3, v2
	v_min_u32_e32 v2, v3, v2
	v_max_u32_e32 v31, v33, v32
	v_min_u32_e32 v32, v33, v32
	v_min_u32_e32 v34, v34, v35
	v_max_u32_e32 v35, v37, v36
	v_min_u32_e32 v36, v37, v36
	v_max_u32_e32 v7, v0, v1
	v_min_u32_e32 v0, v0, v1
	v_max_u32_e32 v1, v40, v39
	v_min_u32_e32 v39, v40, v39
	v_max_u32_e32 v3, v41, v48
	v_min_u32_e32 v41, v41, v48
	v_max_u32_e32 v48, v46, v47
	v_min_u32_e32 v46, v46, v47
	v_max_u32_e32 v47, v43, v49
	v_min_u32_e32 v43, v43, v49
	v_max_u32_e32 v49, v42, v29
	v_min_u32_e32 v29, v42, v29
	v_max_u32_e32 v42, v44, v58
	v_min_u32_e32 v44, v44, v58
	v_max_u32_e32 v58, v45, v55
	v_min_u32_e32 v45, v45, v55
	v_max_u32_e32 v55, v2, v61
	v_min_u32_e32 v2, v2, v61
	v_max_u32_e32 v61, v64, v38
	v_min_u32_e32 v38, v64, v38
	v_max_u32_e32 v33, v72, v26
	v_min_u32_e32 v26, v72, v26
	v_max_u32_e32 v72, v22, v24
	v_min_u32_e32 v22, v22, v24
	v_max_u32_e32 v24, v52, v28
	v_min_u32_e32 v28, v52, v28
	v_max_u32_e32 v52, v51, v50
	v_min_u32_e32 v50, v51, v50
	v_max_u32_e32 v51, v53, v59
	v_min_u32_e32 v53, v53, v59
	v_max_u32_e32 v59, v54, v56
	v_min_u32_e32 v54, v54, v56
	v_max_u32_e32 v56, v32, v62
	v_min_u32_e32 v32, v32, v62
	v_max_u32_e32 v62, v31, v30
	v_min_u32_e32 v30, v31, v30
	v_max_u32_e32 v37, v80, v18
	v_min_u32_e32 v18, v80, v18
	v_max_u32_e32 v80, v14, v16
	v_min_u32_e32 v14, v14, v16
	v_max_u32_e32 v16, v23, v19
	v_min_u32_e32 v19, v23, v19
	v_max_u32_e32 v23, v21, v20
	v_min_u32_e32 v20, v21, v20
	v_max_u32_e32 v21, v25, v60
	v_min_u32_e32 v25, v25, v60
	v_max_u32_e32 v60, v27, v57
	v_min_u32_e32 v27, v27, v57
	v_max_u32_e32 v57, v36, v63
	v_min_u32_e32 v36, v36, v63
	v_max_u32_e32 v63, v35, v34
	v_min_u32_e32 v34, v35, v34
	v_max_u32_e32 v40, v88, v10
	v_min_u32_e32 v10, v88, v10
	v_max_u32_e32 v88, v8, v9
	v_min_u32_e32 v8, v8, v9
	v_max_u32_e32 v9, v15, v11
	v_min_u32_e32 v11, v15, v11
	v_max_u32_e32 v15, v13, v12
	v_min_u32_e32 v12, v13, v12
	v_max_u32_e32 v13, v17, v6
	v_min_u32_e32 v6, v17, v6
	v_max_u32_e32 v17, v4, v5
	v_min_u32_e32 v4, v4, v5
	v_max_u32_e32 v5, v39, v7
	v_min_u32_e32 v7, v39, v7
	v_max_u32_e32 v39, v1, v0
	v_min_u32_e32 v0, v1, v0
	v_max_u32_e32 v64, v3, v48
	v_min_u32_e32 v3, v3, v48
	v_max_u32_e32 v48, v41, v46
	v_min_u32_e32 v41, v41, v46
	v_max_u32_e32 v46, v29, v43
	v_min_u32_e32 v29, v29, v43
	v_max_u32_e32 v43, v49, v47
	v_min_u32_e32 v47, v49, v47
	v_max_u32_e32 v49, v42, v58
	v_min_u32_e32 v42, v42, v58
	v_max_u32_e32 v58, v44, v45
	v_min_u32_e32 v44, v44, v45
	v_max_u32_e32 v45, v38, v2
	v_min_u32_e32 v2, v38, v2
	v_max_u32_e32 v38, v61, v55
	v_min_u32_e32 v55, v61, v55
	v_max_u32_e32 v31, v33, v72
	v_min_u32_e32 v33, v33, v72
	v_max_u32_e32 v72, v26, v22
	v_min_u32_e32 v22, v26, v22
	v_max_u32_e32 v26, v50, v28
	v_min_u32_e32 v28, v50, v28
	v_max_u32_e32 v50, v52, v24
	v_min_u32_e32 v24, v52, v24
	v_max_u32_e32 v52, v51, v59
	v_min_u32_e32 v51, v51, v59
	v_max_u32_e32 v59, v53, v54
	v_min_u32_e32 v53, v53, v54
	v_max_u32_e32 v54, v30, v32
	v_min_u32_e32 v30, v30, v32
	v_max_u32_e32 v32, v62, v56
	v_min_u32_e32 v56, v62, v56
	v_max_u32_e32 v35, v37, v80
	v_min_u32_e32 v37, v37, v80
	v_max_u32_e32 v80, v18, v14
	v_min_u32_e32 v14, v18, v14
	v_max_u32_e32 v18, v20, v19
	v_min_u32_e32 v19, v20, v19
	v_max_u32_e32 v20, v23, v16
	v_min_u32_e32 v16, v23, v16
	v_max_u32_e32 v23, v21, v60
	v_min_u32_e32 v21, v21, v60
	v_max_u32_e32 v60, v25, v27
	v_min_u32_e32 v25, v25, v27
	v_max_u32_e32 v27, v34, v36
	v_min_u32_e32 v34, v34, v36
	v_max_u32_e32 v36, v63, v57
	v_min_u32_e32 v57, v63, v57
	v_max_u32_e32 v1, v40, v88
	v_min_u32_e32 v40, v40, v88
	v_max_u32_e32 v88, v10, v8
	v_min_u32_e32 v8, v10, v8
	v_max_u32_e32 v10, v12, v11
	v_min_u32_e32 v11, v12, v11
	v_max_u32_e32 v12, v15, v9
	v_min_u32_e32 v9, v15, v9
	v_max_u32_e32 v15, v13, v17
	v_min_u32_e32 v13, v13, v17
	v_max_u32_e32 v17, v6, v4
	v_min_u32_e32 v4, v6, v4
	v_max_u32_e32 v6, v0, v7
	v_min_u32_e32 v0, v0, v7
	v_max_u32_e32 v7, v39, v5
	v_min_u32_e32 v5, v39, v5
	v_max_u32_e32 v61, v64, v29
	v_min_u32_e32 v29, v64, v29
	v_max_u32_e32 v64, v3, v46
	v_min_u32_e32 v3, v3, v46
	v_max_u32_e32 v46, v48, v47
	v_min_u32_e32 v47, v48, v47
	v_max_u32_e32 v48, v41, v43
	v_min_u32_e32 v41, v41, v43
	v_max_u32_e32 v43, v2, v49
	v_min_u32_e32 v2, v2, v49
	v_max_u32_e32 v49, v45, v42
	v_min_u32_e32 v42, v45, v42
	v_max_u32_e32 v45, v55, v58
	v_min_u32_e32 v55, v55, v58
	v_max_u32_e32 v58, v38, v44
	v_min_u32_e32 v38, v38, v44
	v_max_u32_e32 v62, v31, v28
	v_min_u32_e32 v28, v31, v28
	v_max_u32_e32 v31, v33, v26
	v_min_u32_e32 v26, v33, v26
	v_max_u32_e32 v33, v72, v24
	v_min_u32_e32 v24, v72, v24
	v_max_u32_e32 v72, v22, v50
	v_min_u32_e32 v22, v22, v50
	v_max_u32_e32 v50, v30, v52
	v_min_u32_e32 v30, v30, v52
	v_max_u32_e32 v52, v54, v51
	v_min_u32_e32 v51, v54, v51
	v_max_u32_e32 v54, v56, v59
	v_min_u32_e32 v56, v56, v59
	v_max_u32_e32 v59, v32, v53
	v_min_u32_e32 v32, v32, v53
	v_max_u32_e32 v63, v35, v19
	v_min_u32_e32 v19, v35, v19
	v_max_u32_e32 v35, v37, v18
	v_min_u32_e32 v18, v37, v18
	v_max_u32_e32 v37, v80, v16
	v_min_u32_e32 v16, v80, v16
	v_max_u32_e32 v80, v14, v20
	v_min_u32_e32 v14, v14, v20
	v_max_u32_e32 v20, v34, v23
	v_min_u32_e32 v23, v34, v23
	v_max_u32_e32 v34, v27, v21
	v_min_u32_e32 v21, v27, v21
	v_max_u32_e32 v27, v57, v60
	v_min_u32_e32 v57, v57, v60
	v_max_u32_e32 v60, v36, v25
	v_min_u32_e32 v25, v36, v25
	v_max_u32_e32 v39, v1, v11
	v_min_u32_e32 v1, v1, v11
	v_max_u32_e32 v11, v40, v10
	v_min_u32_e32 v10, v40, v10
	v_max_u32_e32 v40, v88, v9
	v_min_u32_e32 v9, v88, v9
	v_max_u32_e32 v88, v8, v12
	v_min_u32_e32 v8, v8, v12
	v_max_u32_e32 v12, v0, v15
	v_min_u32_e32 v0, v0, v15
	v_max_u32_e32 v15, v6, v13
	v_min_u32_e32 v6, v6, v13
	v_max_u32_e32 v13, v5, v17
	v_min_u32_e32 v5, v5, v17
	v_max_u32_e32 v17, v7, v4
	v_min_u32_e32 v4, v7, v4
	v_max_u32_e32 v44, v61, v46
	v_min_u32_e32 v46, v61, v46
	v_max_u32_e32 v61, v64, v48
	v_min_u32_e32 v48, v64, v48
	v_max_u32_e32 v64, v29, v47
	v_min_u32_e32 v29, v29, v47
	v_max_u32_e32 v47, v3, v41
	v_min_u32_e32 v3, v3, v41
	v_max_u32_e32 v41, v55, v2
	v_min_u32_e32 v2, v55, v2
	v_max_u32_e32 v55, v38, v42
	v_min_u32_e32 v38, v38, v42
	v_max_u32_e32 v42, v45, v43
	v_min_u32_e32 v43, v45, v43
	v_max_u32_e32 v45, v58, v49
	v_min_u32_e32 v49, v58, v49
	v_max_u32_e32 v53, v62, v33
	v_min_u32_e32 v33, v62, v33
	v_max_u32_e32 v62, v31, v72
	v_min_u32_e32 v31, v31, v72
	v_max_u32_e32 v72, v28, v24
	v_min_u32_e32 v24, v28, v24
	v_max_u32_e32 v28, v26, v22
	v_min_u32_e32 v22, v26, v22
	v_max_u32_e32 v26, v56, v30
	v_min_u32_e32 v30, v56, v30
	v_max_u32_e32 v56, v32, v51
	v_min_u32_e32 v32, v32, v51
	v_max_u32_e32 v51, v54, v50
	v_min_u32_e32 v50, v54, v50
	v_max_u32_e32 v54, v59, v52
	v_min_u32_e32 v52, v59, v52
	v_max_u32_e32 v36, v63, v37
	v_min_u32_e32 v37, v63, v37
	v_max_u32_e32 v63, v35, v80
	v_min_u32_e32 v35, v35, v80
	v_max_u32_e32 v80, v19, v16
	v_min_u32_e32 v16, v19, v16
	v_max_u32_e32 v19, v18, v14
	v_min_u32_e32 v14, v18, v14
	v_max_u32_e32 v18, v57, v23
	v_min_u32_e32 v23, v57, v23
	v_max_u32_e32 v57, v25, v21
	v_min_u32_e32 v21, v25, v21
	v_max_u32_e32 v25, v27, v20
	v_min_u32_e32 v20, v27, v20
	v_max_u32_e32 v27, v60, v34
	v_min_u32_e32 v34, v60, v34
	v_max_u32_e32 v7, v39, v40
	v_min_u32_e32 v39, v39, v40
	v_max_u32_e32 v40, v11, v88
	v_min_u32_e32 v11, v11, v88
	v_max_u32_e32 v88, v1, v9
	v_min_u32_e32 v1, v1, v9
	v_max_u32_e32 v9, v10, v8
	v_min_u32_e32 v8, v10, v8
	v_max_u32_e32 v10, v5, v0
	v_min_u32_e32 v0, v5, v0
	v_max_u32_e32 v5, v4, v6
	v_min_u32_e32 v4, v4, v6
	v_max_u32_e32 v6, v13, v12
	v_min_u32_e32 v12, v13, v12
	v_max_u32_e32 v13, v17, v15
	v_min_u32_e32 v15, v17, v15
	v_max_u32_e32 v58, v44, v61
	v_min_u32_e32 v44, v44, v61
	v_max_u32_e32 v61, v46, v48
	v_min_u32_e32 v46, v46, v48
	v_max_u32_e32 v48, v64, v47
	v_min_u32_e32 v47, v64, v47
	v_max_u32_e32 v64, v29, v3
	v_min_u32_e32 v3, v29, v3
	v_max_u32_e32 v29, v38, v2
	v_min_u32_e32 v2, v38, v2
	v_max_u32_e32 v38, v55, v41
	v_min_u32_e32 v41, v55, v41
	v_max_u32_e32 v55, v49, v43
	v_min_u32_e32 v43, v49, v43
	v_max_u32_e32 v49, v45, v42
	v_min_u32_e32 v42, v45, v42
	v_max_u32_e32 v59, v53, v62
	v_min_u32_e32 v53, v53, v62
	v_max_u32_e32 v62, v33, v31
	v_min_u32_e32 v31, v33, v31
	v_max_u32_e32 v33, v72, v28
	v_min_u32_e32 v28, v72, v28
	v_max_u32_e32 v72, v24, v22
	v_min_u32_e32 v22, v24, v22
	v_max_u32_e32 v24, v32, v30
	v_min_u32_e32 v30, v32, v30
	v_max_u32_e32 v32, v56, v26
	v_min_u32_e32 v26, v56, v26
	v_max_u32_e32 v56, v52, v50
	v_min_u32_e32 v50, v52, v50
	v_max_u32_e32 v52, v54, v51
	v_min_u32_e32 v51, v54, v51
	v_max_u32_e32 v60, v36, v63
	v_min_u32_e32 v36, v36, v63
	v_max_u32_e32 v63, v37, v35
	v_min_u32_e32 v35, v37, v35
	v_max_u32_e32 v37, v80, v19
	v_min_u32_e32 v19, v80, v19
	v_max_u32_e32 v80, v16, v14
	v_min_u32_e32 v14, v16, v14
	v_max_u32_e32 v16, v21, v23
	v_min_u32_e32 v21, v21, v23
	v_max_u32_e32 v23, v57, v18
	v_min_u32_e32 v18, v57, v18
	v_max_u32_e32 v57, v34, v20
	v_min_u32_e32 v20, v34, v20
	v_max_u32_e32 v34, v27, v25
	v_min_u32_e32 v25, v27, v25
	v_max_u32_e32 v17, v7, v40
	v_min_u32_e32 v7, v7, v40
	v_max_u32_e32 v40, v39, v11
	v_min_u32_e32 v11, v39, v11
	v_max_u32_e32 v39, v88, v9
	v_min_u32_e32 v9, v88, v9
	v_max_u32_e32 v88, v1, v8
	v_min_u32_e32 v1, v1, v8
	v_max_u32_e32 v8, v4, v0
	v_min_u32_e32 v0, v4, v0
	v_max_u32_e32 v4, v5, v10
	v_min_u32_e32 v5, v5, v10
	v_max_u32_e32 v10, v15, v12
	v_min_u32_e32 v12, v15, v12
	v_max_u32_e32 v15, v13, v6
	v_min_u32_e32 v6, v13, v6
	v_max_u32_e32 v45, v58, v2
	v_min_u32_e32 v2, v58, v2
	v_max_u32_e32 v58, v44, v29
	v_min_u32_e32 v29, v44, v29
	v_max_u32_e32 v44, v61, v41
	v_min_u32_e32 v41, v61, v41
	v_max_u32_e32 v61, v46, v38
	v_min_u32_e32 v38, v46, v38
	v_max_u32_e32 v46, v48, v43
	v_min_u32_e32 v43, v48, v43
	v_max_u32_e32 v48, v47, v55
	v_min_u32_e32 v47, v47, v55
	v_max_u32_e32 v55, v64, v42
	v_min_u32_e32 v42, v64, v42
	v_max_u32_e32 v64, v3, v49
	v_min_u32_e32 v3, v3, v49
	v_max_u32_e32 v54, v59, v30
	v_min_u32_e32 v30, v59, v30
	v_max_u32_e32 v59, v53, v24
	v_min_u32_e32 v24, v53, v24
	v_max_u32_e32 v53, v62, v26
	v_min_u32_e32 v26, v62, v26
	v_max_u32_e32 v62, v31, v32
	v_min_u32_e32 v31, v31, v32
	v_max_u32_e32 v32, v33, v50
	v_min_u32_e32 v33, v33, v50
	v_max_u32_e32 v50, v28, v56
	v_min_u32_e32 v28, v28, v56
	v_max_u32_e32 v56, v72, v51
	v_min_u32_e32 v51, v72, v51
	v_max_u32_e32 v72, v22, v52
	v_min_u32_e32 v22, v22, v52
	v_max_u32_e32 v27, v60, v21
	v_min_u32_e32 v21, v60, v21
	v_max_u32_e32 v60, v36, v16
	v_min_u32_e32 v16, v36, v16
	v_max_u32_e32 v36, v63, v18
	v_min_u32_e32 v18, v63, v18
	v_max_u32_e32 v63, v35, v23
	v_min_u32_e32 v23, v35, v23
	v_max_u32_e32 v35, v37, v20
	v_min_u32_e32 v20, v37, v20
	v_max_u32_e32 v37, v19, v57
	v_min_u32_e32 v19, v19, v57
	v_max_u32_e32 v57, v80, v25
	v_min_u32_e32 v25, v80, v25
	v_max_u32_e32 v80, v14, v34
	v_min_u32_e32 v14, v14, v34
	v_max_u32_e32 v13, v17, v0
	v_min_u32_e32 v0, v17, v0
	v_max_u32_e32 v17, v7, v8
	v_min_u32_e32 v7, v7, v8
	v_max_u32_e32 v8, v40, v5
	v_min_u32_e32 v5, v40, v5
	v_max_u32_e32 v40, v11, v4
	v_min_u32_e32 v4, v11, v4
	v_max_u32_e32 v11, v39, v12
	v_min_u32_e32 v12, v39, v12
	v_max_u32_e32 v39, v9, v10
	v_min_u32_e32 v9, v9, v10
	v_max_u32_e32 v10, v88, v6
	v_min_u32_e32 v6, v88, v6
	v_max_u32_e32 v88, v1, v15
	v_min_u32_e32 v1, v1, v15
	v_max_u32_e32 v49, v45, v46
	v_min_u32_e32 v45, v45, v46
	v_max_u32_e32 v46, v58, v48
	v_min_u32_e32 v48, v58, v48
	v_max_u32_e32 v58, v44, v55
	v_min_u32_e32 v44, v44, v55
	v_max_u32_e32 v55, v61, v64
	v_min_u32_e32 v61, v61, v64
	v_max_u32_e32 v64, v2, v43
	v_min_u32_e32 v43, v2, v43
	v_max_u32_e32 v65, v29, v47
	v_min_u32_e32 v29, v29, v47
	v_max_u32_e32 v47, v41, v42
	v_min_u32_e32 v41, v41, v42
	v_max_u32_e32 v42, v38, v3
	v_min_u32_e32 v38, v38, v3
	v_max_u32_e32 v52, v54, v32
	v_min_u32_e32 v32, v54, v32
	v_max_u32_e32 v54, v59, v50
	v_min_u32_e32 v50, v59, v50
	v_max_u32_e32 v59, v53, v56
	v_min_u32_e32 v53, v53, v56
	v_max_u32_e32 v56, v62, v72
	v_min_u32_e32 v62, v62, v72
	v_max_u32_e32 v72, v30, v33
	v_min_u32_e32 v30, v30, v33
	v_max_u32_e32 v33, v24, v28
	v_min_u32_e32 v24, v24, v28
	v_max_u32_e32 v28, v26, v51
	v_min_u32_e32 v26, v26, v51
	v_max_u32_e32 v51, v31, v22
	v_min_u32_e32 v22, v31, v22
	v_max_u32_e32 v34, v27, v35
	v_min_u32_e32 v27, v27, v35
	v_max_u32_e32 v35, v60, v37
	v_min_u32_e32 v37, v60, v37
	v_max_u32_e32 v60, v36, v57
	v_min_u32_e32 v36, v36, v57
	v_max_u32_e32 v57, v63, v80
	v_min_u32_e32 v63, v63, v80
	v_max_u32_e32 v80, v21, v20
	v_min_u32_e32 v20, v21, v20
	v_max_u32_e32 v21, v16, v19
	v_min_u32_e32 v16, v16, v19
	v_max_u32_e32 v19, v18, v25
	v_min_u32_e32 v18, v18, v25
	v_max_u32_e32 v25, v23, v14
	v_min_u32_e32 v14, v23, v14
	v_max_u32_e32 v15, v13, v11
	v_min_u32_e32 v11, v13, v11
	v_max_u32_e32 v13, v17, v39
	v_min_u32_e32 v17, v17, v39
	v_max_u32_e32 v39, v8, v10
	v_min_u32_e32 v8, v8, v10
	v_max_u32_e32 v10, v40, v88
	v_min_u32_e32 v40, v40, v88
	v_max_u32_e32 v88, v0, v12
	v_min_u32_e32 v0, v0, v12
	v_max_u32_e32 v12, v7, v9
	v_min_u32_e32 v7, v7, v9
	v_max_u32_e32 v9, v5, v6
	v_min_u32_e32 v5, v5, v6
	v_max_u32_e32 v6, v4, v1
	v_min_u32_e32 v1, v4, v1
	v_max_u32_e32 v2, v49, v58
	v_min_u32_e32 v49, v49, v58
	v_max_u32_e32 v3, v46, v55
	v_min_u32_e32 v46, v46, v55
	v_max_u32_e32 v55, v45, v44
	v_min_u32_e32 v44, v45, v44
	v_max_u32_e32 v45, v48, v61
	v_min_u32_e32 v48, v48, v61
	v_max_u32_e32 v58, v64, v47
	v_min_u32_e32 v47, v64, v47
	v_max_u32_e32 v61, v65, v42
	v_min_u32_e32 v42, v65, v42
	v_max_u32_e32 v64, v43, v41
	v_min_u32_e32 v41, v43, v41
	v_max_u32_e32 v43, v29, v38
	v_min_u32_e32 v29, v29, v38
	v_max_u32_e32 v31, v52, v59
	v_min_u32_e32 v52, v52, v59
	v_max_u32_e32 v59, v54, v56
	v_min_u32_e32 v54, v54, v56
	v_max_u32_e32 v56, v32, v53
	v_min_u32_e32 v32, v32, v53
	v_max_u32_e32 v53, v50, v62
	v_min_u32_e32 v50, v50, v62
	v_max_u32_e32 v62, v72, v28
	v_min_u32_e32 v28, v72, v28
	v_max_u32_e32 v72, v33, v51
	v_min_u32_e32 v33, v33, v51
	v_max_u32_e32 v51, v30, v26
	v_min_u32_e32 v26, v30, v26
	v_max_u32_e32 v30, v24, v22
	v_min_u32_e32 v22, v24, v22
	v_max_u32_e32 v23, v34, v60
	v_min_u32_e32 v34, v34, v60
	v_max_u32_e32 v60, v35, v57
	v_min_u32_e32 v35, v35, v57
	v_max_u32_e32 v57, v27, v36
	v_min_u32_e32 v27, v27, v36
	v_max_u32_e32 v36, v37, v63
	v_min_u32_e32 v37, v37, v63
	v_max_u32_e32 v63, v80, v19
	v_min_u32_e32 v19, v80, v19
	v_max_u32_e32 v80, v21, v25
	v_min_u32_e32 v21, v21, v25
	v_max_u32_e32 v25, v20, v18
	v_min_u32_e32 v18, v20, v18
	v_max_u32_e32 v20, v16, v14
	v_min_u32_e32 v14, v16, v14
	v_max_u32_e32 v4, v15, v39
	v_min_u32_e32 v15, v15, v39
	v_max_u32_e32 v39, v13, v10
	v_min_u32_e32 v10, v13, v10
	v_max_u32_e32 v13, v11, v8
	v_min_u32_e32 v8, v11, v8
	v_max_u32_e32 v11, v17, v40
	v_min_u32_e32 v17, v17, v40
	v_max_u32_e32 v40, v88, v9
	v_min_u32_e32 v9, v88, v9
	v_max_u32_e32 v88, v12, v6
	v_min_u32_e32 v6, v12, v6
	v_max_u32_e32 v12, v0, v5
	v_min_u32_e32 v0, v0, v5
	v_max_u32_e32 v5, v7, v1
	v_min_u32_e32 v1, v7, v1
	v_min_u32_e32 v38, v2, v3
	v_min_u32_e32 v65, v49, v46
	v_min_u32_e32 v66, v55, v45
	v_min_u32_e32 v67, v44, v48
	v_min_u32_e32 v68, v58, v61
	v_min_u32_e32 v69, v47, v42
	v_min_u32_e32 v70, v64, v43
	v_min_u32_e32 v71, v41, v29
	v_min_u32_e32 v24, v31, v59
	v_min_u32_e32 v73, v52, v54
	v_min_u32_e32 v74, v56, v53
	v_min_u32_e32 v75, v32, v50
	v_min_u32_e32 v76, v62, v72
	v_min_u32_e32 v77, v28, v33
	v_min_u32_e32 v78, v51, v30
	v_min_u32_e32 v79, v26, v22
	v_min_u32_e32 v16, v23, v60
	v_min_u32_e32 v81, v34, v35
	v_min_u32_e32 v82, v57, v36
	v_min_u32_e32 v83, v27, v37
	v_min_u32_e32 v84, v63, v80
	v_min_u32_e32 v85, v19, v21
	v_min_u32_e32 v86, v25, v20
	v_min_u32_e32 v87, v18, v14
	v_min_u32_e32 v7, v4, v39
	v_min_u32_e32 v89, v15, v10
	v_min_u32_e32 v90, v13, v11
	v_min_u32_e32 v91, v8, v17
	v_min_u32_e32 v92, v40, v88
	v_min_u32_e32 v93, v9, v6
	v_min_u32_e32 v94, v12, v5
	v_min_u32_e32 v95, v0, v1
	v_max3_u32 v23, v23, v60, v95
	v_max3_u32 v22, v38, v26, v22
	v_max3_u32 v0, v16, v0, v1
	v_max3_u32 v1, v49, v46, v78
	v_max3_u32 v16, v34, v35, v94
	v_max3_u32 v26, v65, v51, v30
	v_max3_u32 v5, v81, v12, v5
	v_max3_u32 v12, v55, v45, v77
	v_max3_u32 v30, v57, v36, v93
	v_max3_u32 v28, v66, v28, v33
	v_max3_u32 v6, v82, v9, v6
	v_max3_u32 v9, v44, v48, v76
	v_max3_u32 v27, v27, v37, v92
	v_max3_u32 v33, v67, v62, v72
	v_max3_u32 v34, v83, v40, v88
	v_max3_u32 v35, v63, v80, v91
	v_max3_u32 v32, v68, v32, v50
	v_max3_u32 v8, v84, v8, v17
	v_max3_u32 v17, v47, v42, v74
	v_max3_u32 v19, v19, v21, v90
	v_max3_u32 v21, v69, v56, v53
	v_max3_u32 v11, v85, v13, v11
	v_max3_u32 v13, v64, v43, v73
	v_max3_u32 v20, v25, v20, v89
	v_max3_u32 v25, v70, v52, v54
	v_max3_u32 v10, v86, v15, v10
	v_max3_u32 v15, v41, v29, v24
	v_max3_u32 v7, v18, v14, v7
	v_max3_u32 v14, v71, v31, v59
	v_max3_u32 v4, v87, v4, v39
	v_max3_u32 v18, v58, v61, v75
	v_max3_u32 v2, v2, v3, v79
	v_max_u32_e32 v3, v2, v18
	v_min_u32_e32 v2, v2, v18
	v_max_u32_e32 v18, v22, v32
	v_min_u32_e32 v22, v22, v32
	v_max_u32_e32 v24, v1, v17
	v_min_u32_e32 v1, v1, v17
	v_max_u32_e32 v17, v26, v21
	v_min_u32_e32 v21, v26, v21
	v_max_u32_e32 v26, v12, v13
	v_min_u32_e32 v12, v12, v13
	v_max_u32_e32 v13, v28, v25
	v_min_u32_e32 v25, v28, v25
	v_max_u32_e32 v28, v9, v15
	v_min_u32_e32 v9, v9, v15
	v_max_u32_e32 v15, v33, v14
	v_min_u32_e32 v14, v33, v14
	v_max_u32_e32 v40, v23, v35
	v_min_u32_e32 v23, v23, v35
	v_max_u32_e32 v35, v0, v8
	v_min_u32_e32 v0, v0, v8
	v_max_u32_e32 v8, v16, v19
	v_min_u32_e32 v16, v16, v19
	v_max_u32_e32 v19, v5, v11
	v_min_u32_e32 v5, v5, v11
	v_max_u32_e32 v11, v30, v20
	v_min_u32_e32 v20, v30, v20
	v_max_u32_e32 v30, v6, v10
	v_min_u32_e32 v6, v6, v10
	v_max_u32_e32 v10, v27, v7
	v_min_u32_e32 v7, v27, v7
	v_max_u32_e32 v27, v34, v4
	v_min_u32_e32 v4, v34, v4
	v_max_u32_e32 v29, v3, v26
	v_min_u32_e32 v3, v3, v26
	v_max_u32_e32 v26, v18, v13
	v_min_u32_e32 v13, v18, v13
	v_max_u32_e32 v18, v24, v28
	v_min_u32_e32 v24, v24, v28
	v_max_u32_e32 v28, v17, v15
	v_min_u32_e32 v15, v17, v15
	v_max_u32_e32 v17, v2, v12
	v_min_u32_e32 v2, v2, v12
	v_max_u32_e32 v12, v22, v25
	v_min_u32_e32 v22, v22, v25
	v_max_u32_e32 v25, v1, v9
	v_min_u32_e32 v1, v1, v9
	v_max_u32_e32 v9, v21, v14
	v_min_u32_e32 v14, v21, v14
	v_max_u32_e32 v34, v40, v11
	v_min_u32_e32 v11, v40, v11
	v_max_u32_e32 v40, v35, v30
	v_min_u32_e32 v30, v35, v30
	v_max_u32_e32 v35, v8, v10
	v_min_u32_e32 v8, v8, v10
	v_max_u32_e32 v10, v19, v27
	v_min_u32_e32 v19, v19, v27
	v_max_u32_e32 v27, v23, v20
	v_min_u32_e32 v20, v23, v20
	v_max_u32_e32 v23, v0, v6
	v_min_u32_e32 v0, v0, v6
	v_max_u32_e32 v6, v16, v7
	v_min_u32_e32 v7, v16, v7
	v_max_u32_e32 v16, v5, v4
	v_min_u32_e32 v4, v5, v4
	v_max_u32_e32 v21, v29, v18
	v_min_u32_e32 v18, v29, v18
	v_max_u32_e32 v29, v26, v28
	v_min_u32_e32 v26, v26, v28
	v_max_u32_e32 v28, v3, v24
	v_min_u32_e32 v3, v3, v24
	v_max_u32_e32 v24, v13, v15
	v_min_u32_e32 v13, v13, v15
	v_max_u32_e32 v15, v17, v25
	v_min_u32_e32 v17, v17, v25
	v_max_u32_e32 v25, v12, v9
	v_min_u32_e32 v9, v12, v9
	v_max_u32_e32 v12, v2, v1
	v_min_u32_e32 v1, v2, v1
	v_max_u32_e32 v2, v22, v14
	v_min_u32_e32 v14, v22, v14
	v_max_u32_e32 v5, v34, v35
	v_min_u32_e32 v34, v34, v35
	v_max_u32_e32 v35, v40, v10
	v_min_u32_e32 v10, v40, v10
	v_max_u32_e32 v40, v11, v8
	v_min_u32_e32 v8, v11, v8
	v_max_u32_e32 v11, v30, v19
	v_min_u32_e32 v19, v30, v19
	v_max_u32_e32 v30, v27, v6
	v_min_u32_e32 v6, v27, v6
	v_max_u32_e32 v27, v23, v16
	v_min_u32_e32 v16, v23, v16
	v_max_u32_e32 v23, v20, v7
	v_min_u32_e32 v7, v20, v7
	v_max_u32_e32 v20, v0, v4
	v_min_u32_e32 v0, v0, v4
	v_min_u32_e32 v22, v21, v29
	v_min_u32_e32 v31, v18, v26
	v_min_u32_e32 v32, v28, v24
	v_min_u32_e32 v33, v3, v13
	v_min_u32_e32 v36, v15, v25
	v_min_u32_e32 v37, v17, v9
	v_min_u32_e32 v38, v12, v2
	v_min_u32_e32 v39, v1, v14
	v_min_u32_e32 v4, v5, v35
	v_min_u32_e32 v41, v34, v10
	v_min_u32_e32 v42, v40, v11
	v_min_u32_e32 v43, v8, v19
	v_min_u32_e32 v44, v30, v27
	v_min_u32_e32 v45, v6, v16
	v_min_u32_e32 v46, v23, v20
	v_min_u32_e32 v47, v7, v0
	v_max3_u32 v0, v22, v7, v0
	v_max3_u32 v7, v18, v26, v46
	v_max3_u32 v18, v31, v23, v20
	v_max3_u32 v20, v28, v24, v45
	v_max3_u32 v6, v32, v6, v16
	v_max3_u32 v3, v3, v13, v44
	v_max3_u32 v13, v33, v30, v27
	v_max3_u32 v8, v36, v8, v19
	v_max3_u32 v9, v17, v9, v42
	v_max3_u32 v11, v37, v40, v11
	v_max3_u32 v2, v12, v2, v41
	v_max3_u32 v10, v38, v34, v10
	v_max3_u32 v1, v1, v14, v4
	v_max3_u32 v4, v39, v5, v35
	v_max3_u32 v5, v15, v25, v43
	v_max3_u32 v12, v21, v29, v47
	v_max_u32_e32 v14, v12, v5
	v_min_u32_e32 v5, v12, v5
	v_max_u32_e32 v12, v0, v8
	v_min_u32_e32 v0, v0, v8
	v_max_u32_e32 v8, v7, v9
	v_min_u32_e32 v7, v7, v9
	v_max_u32_e32 v9, v18, v11
	v_max_u32_e32 v15, v20, v2
	v_max_u32_e32 v16, v6, v10
	v_min_u32_e32 v6, v6, v10
	v_max_u32_e32 v10, v3, v1
	v_min_u32_e32 v1, v3, v1
	v_max_u32_e32 v3, v13, v4
	v_min_u32_e32 v11, v18, v11
	v_min_u32_e32 v2, v20, v2
	v_min_u32_e32 v4, v13, v4
	v_max_u32_e32 v13, v14, v15
	v_min_u32_e32 v14, v14, v15
	v_max_u32_e32 v15, v12, v16
	v_min_u32_e32 v12, v12, v16
	v_max_u32_e32 v16, v8, v10
	v_min_u32_e32 v8, v8, v10
	v_max_u32_e32 v10, v9, v3
	v_min_u32_e32 v3, v9, v3
	v_max_u32_e32 v9, v5, v2
	v_min_u32_e32 v2, v5, v2
	v_max_u32_e32 v5, v0, v6
	v_min_u32_e32 v0, v0, v6
	v_max_u32_e32 v6, v7, v1
	v_min_u32_e32 v1, v7, v1
	v_max_u32_e32 v7, v11, v4
	v_min_u32_e32 v4, v11, v4
	v_max_u32_e32 v11, v13, v16
	v_min_u32_e32 v13, v13, v16
	v_max_u32_e32 v16, v15, v10
	v_cmp_lt_i32_e64 s[0:1], v120, v121
	v_min_u32_e32 v10, v15, v10
	v_max_u32_e32 v15, v14, v8
	v_min_u32_e32 v8, v14, v8
	v_max_u32_e32 v14, v12, v3
	v_min_u32_e32 v3, v12, v3
	v_max_u32_e32 v18, v2, v1
	v_min_u32_e32 v19, v2, v1
	v_max_u32_e32 v20, v0, v4
	v_min_u32_e32 v21, v0, v4
	v_max_u32_e32 v0, v11, v16
	v_min_u32_e32 v1, v11, v16
	v_cndmask_b32_e64 v16, v215, v120, s[0:1]
	v_max_u32_e32 v12, v9, v6
	v_min_u32_e32 v6, v9, v6
	v_max_u32_e32 v9, v5, v7
	v_min_u32_e32 v17, v5, v7
	v_max_u32_e32 v5, v15, v14
	v_min_u32_e32 v7, v15, v14
	v_max_u32_e32 v11, v8, v3
	v_min_u32_e32 v14, v8, v3
	v_max_u32_e32 v8, v19, v21
	v_lshlrev_b32_e32 v16, 2, v16
	v_max_u32_e32 v2, v13, v10
	v_min_u32_e32 v4, v13, v10
	v_max_u32_e32 v3, v12, v9
	v_min_u32_e32 v15, v12, v9
	v_max_u32_e32 v10, v18, v20
	v_min_u32_e32 v9, v18, v20
	ds_bpermute_b32 v18, v16, v8
	v_max_u32_e32 v13, v6, v17
	v_min_u32_e32 v12, v6, v17
	v_min_u32_e32 v6, v19, v21
	ds_bpermute_b32 v19, v16, v9
	s_waitcnt lgkmcnt(1)
	v_max_u32_e32 v18, v1, v18
	ds_bpermute_b32 v20, v16, v10
	ds_bpermute_b32 v21, v16, v12
	ds_bpermute_b32 v22, v16, v13
	ds_bpermute_b32 v23, v16, v15
	ds_bpermute_b32 v24, v16, v3
	ds_bpermute_b32 v1, v16, v1
	ds_bpermute_b32 v17, v16, v6
	s_waitcnt lgkmcnt(7)
	v_max_u32_e32 v19, v2, v19
	s_waitcnt lgkmcnt(6)
	v_max_u32_e32 v20, v4, v20
	s_waitcnt lgkmcnt(5)
	v_max_u32_e32 v21, v5, v21
	s_waitcnt lgkmcnt(4)
	v_max_u32_e32 v22, v7, v22
	s_waitcnt lgkmcnt(3)
	v_max_u32_e32 v23, v11, v23
	s_waitcnt lgkmcnt(2)
	v_max_u32_e32 v24, v14, v24
	ds_bpermute_b32 v14, v16, v14
	ds_bpermute_b32 v11, v16, v11
	ds_bpermute_b32 v7, v16, v7
	ds_bpermute_b32 v5, v16, v5
	ds_bpermute_b32 v4, v16, v4
	ds_bpermute_b32 v2, v16, v2
	s_waitcnt lgkmcnt(7)
	v_max_u32_e32 v1, v8, v1
	ds_bpermute_b32 v8, v16, v0
	s_waitcnt lgkmcnt(5)
	v_max_u32_e32 v11, v15, v11
	s_waitcnt lgkmcnt(4)
	v_max_u32_e32 v7, v13, v7
	s_waitcnt lgkmcnt(3)
	v_max_u32_e32 v5, v12, v5
	s_waitcnt lgkmcnt(2)
	v_max_u32_e32 v4, v10, v4
	s_waitcnt lgkmcnt(1)
	v_max_u32_e32 v2, v9, v2
	s_waitcnt lgkmcnt(0)
	v_max_u32_e32 v6, v6, v8
	v_max_u32_e32 v3, v3, v14
	v_max_u32_e32 v0, v0, v17
	v_max_u32_e32 v8, v0, v3
	v_min_u32_e32 v0, v0, v3
	v_max_u32_e32 v3, v18, v11
	v_min_u32_e32 v9, v18, v11
	v_max_u32_e32 v10, v19, v7
	v_min_u32_e32 v7, v19, v7
	v_max_u32_e32 v11, v20, v5
	v_min_u32_e32 v5, v20, v5
	v_max_u32_e32 v12, v21, v4
	v_min_u32_e32 v4, v21, v4
	v_max_u32_e32 v13, v22, v2
	v_min_u32_e32 v2, v22, v2
	v_max_u32_e32 v14, v23, v1
	v_min_u32_e32 v1, v23, v1
	v_max_u32_e32 v15, v24, v6
	v_min_u32_e32 v6, v24, v6
	v_max_u32_e32 v16, v8, v12
	v_min_u32_e32 v8, v8, v12
	v_max_u32_e32 v12, v3, v13
	v_min_u32_e32 v3, v3, v13
	v_max_u32_e32 v13, v10, v14
	v_min_u32_e32 v10, v10, v14
	v_max_u32_e32 v14, v11, v15
	v_min_u32_e32 v11, v11, v15
	v_max_u32_e32 v15, v0, v4
	v_min_u32_e32 v0, v0, v4
	v_max_u32_e32 v4, v9, v2
	v_min_u32_e32 v2, v9, v2
	v_max_u32_e32 v9, v7, v1
	v_min_u32_e32 v1, v7, v1
	v_max_u32_e32 v7, v5, v6
	v_min_u32_e32 v5, v5, v6
	v_max_u32_e32 v6, v16, v13
	v_min_u32_e32 v13, v16, v13
	v_max_u32_e32 v16, v12, v14
	v_min_u32_e32 v12, v12, v14
	v_max_u32_e32 v14, v8, v10
	v_min_u32_e32 v8, v8, v10
	v_max_u32_e32 v10, v3, v11
	v_min_u32_e32 v3, v3, v11
	v_max_u32_e32 v11, v15, v9
	v_min_u32_e32 v9, v15, v9
	v_max_u32_e32 v15, v4, v7
	v_min_u32_e32 v4, v4, v7
	v_max_u32_e32 v7, v0, v1
	v_min_u32_e32 v0, v0, v1
	v_max_u32_e32 v1, v2, v5
	v_min_u32_e32 v2, v2, v5
	v_max_u32_e32 v5, v6, v16
	v_min_u32_e32 v6, v6, v16
	v_max_u32_e32 v16, v13, v12
	v_min_u32_e32 v12, v13, v12
	v_max_u32_e32 v13, v14, v10
	v_min_u32_e32 v10, v14, v10
	v_max_u32_e32 v14, v8, v3
	v_min_u32_e32 v17, v8, v3
	v_max_u32_e32 v3, v11, v15
	v_min_u32_e32 v8, v11, v15
	v_max_u32_e32 v11, v9, v4
	v_max_u32_e32 v15, v0, v2
	v_min_u32_e32 v18, v0, v2
	v_cndmask_b32_e32 v2, v11, v16, vcc
	v_min_u32_e32 v4, v9, v4
	v_max_u32_e32 v9, v7, v1
	v_min_u32_e32 v7, v7, v1
	v_cndmask_b32_e32 v1, v8, v6, vcc
	v_bitop3_b32 v6, v2, s16, v2 bitop3:0xc
	v_cndmask_b32_e32 v0, v3, v5, vcc
	v_bitop3_b32 v3, v1, s16, v1 bitop3:0xc
	v_lshl_add_u32 v2, v6, 2, v102
	v_lshlrev_b32_e32 v6, 16, v6
	v_lshl_add_u32 v1, v3, 2, v102
	v_lshl_or_b32 v6, v3, 8, v6
	v_cndmask_b32_e32 v3, v4, v12, vcc
	v_bitop3_b32 v4, v3, s16, v3 bitop3:0xc
	v_bitop3_b32 v5, v0, s16, v0 bitop3:0xc
	v_lshl_add_u32 v3, v4, 2, v102
	v_lshlrev_b32_e32 v4, 24, v4
	v_or3_b32 v8, v6, v4, v5
	v_cndmask_b32_e32 v6, v15, v14, vcc
	v_lshl_add_u32 v0, v5, 2, v102
	v_cndmask_b32_e32 v5, v7, v10, vcc
	v_bitop3_b32 v10, v6, s16, v6 bitop3:0xc
	v_bitop3_b32 v7, v5, s16, v5 bitop3:0xc
	v_lshl_add_u32 v6, v10, 2, v102
	v_lshlrev_b32_e32 v10, 16, v10
	v_cndmask_b32_e32 v4, v9, v13, vcc
	v_lshl_add_u32 v5, v7, 2, v102
	v_lshl_or_b32 v10, v7, 8, v10
	v_cndmask_b32_e32 v7, v18, v17, vcc
	v_bitop3_b32 v9, v4, s16, v4 bitop3:0xc
	v_bitop3_b32 v11, v7, s16, v7 bitop3:0xc
	ds_read_b32 v0, v0
	ds_read_b32 v1, v1
	ds_read_b32 v2, v2
	ds_read_b32 v3, v3
	ds_read_b32 v5, v5
	ds_read_b32 v6, v6
	v_lshl_add_u32 v4, v9, 2, v102
	v_lshl_add_u32 v7, v11, 2, v102
	s_lshl_b64 s[0:1], s[12:13], 15
	ds_read_b32 v4, v4
	ds_read_b32 v7, v7
	s_add_u32 s0, s0, s10
	v_lshlrev_b32_e32 v11, 24, v11
	s_addc_u32 s1, s1, s11
	v_or3_b32 v9, v10, v11, v9
	v_lshl_add_u64 v[10:11], s[0:1], 0, v[96:97]
	v_lshl_add_u64 v[12:13], v[10:11], 2, s[22:23]
	s_add_i32 s17, s17, s2
	s_waitcnt lgkmcnt(4)
	global_store_dwordx4 v[12:13], v[0:3], off
	s_waitcnt lgkmcnt(0)
	global_store_dwordx4 v[12:13], v[4:7], off offset:16
	s_cmpk_lt_i32 s17, 0x1000
	v_lshl_add_u64 v[0:1], s[24:25], 0, v[10:11]
	global_store_dwordx2 v[0:1], v[8:9], off
	s_cbranch_scc1 .LBB0_631
